# FFN-up GEMM K-loop: LDS-DMA pieces addressed scalar-base + 32-bit lane offset (no per-piece 64-bit VALU address)
# speedup vs baseline: 1.1452x; 1.0141x over previous
.LBB0_1135:
	ds_read_b128 v[152:155], v149
	ds_read_b128 v[156:159], v149 offset:1024
	ds_read_b128 v[160:163], v149 offset:2048
	ds_read_b128 v[164:167], v149 offset:3072
	ds_read_b128 v[168:171], v150
	ds_read_b128 v[172:175], v150 offset:1024
	ds_read_b128 v[176:179], v150 offset:2048
	ds_read_b128 v[180:183], v150 offset:3072
	s_add_u32 s22, s20, 0xfff80080
	s_addc_u32 s23, s21, -1
	s_cmp_eq_u32 s48, 28
	s_cselect_b32 s25, s13, s23
	s_cselect_b32 s24, s44, s22
	s_cselect_b32 s23, s11, s47
	s_cselect_b32 s22, s45, s46
	s_add_i32 m0, s19, 0xc000
	ds_read_b128 v[184:187], v151
	ds_read_b128 v[188:191], v151 offset:1024
	ds_read_b128 v[192:195], v151 offset:2048
	ds_read_b128 v[196:199], v151 offset:3072
	ds_read_b128 v[200:203], v151 offset:4096
	ds_read_b128 v[204:207], v151 offset:5120
	ds_read_b128 v[208:211], v151 offset:6144
	ds_read_b128 v[212:215], v151 offset:7168
	global_load_lds_dwordx4 v138, s[20:21]
	s_add_i32 m0, s19, 0xe000
	s_nop 0
	global_load_lds_dwordx4 v140, s[20:21]
	s_waitcnt vmcnt(8)
	s_waitcnt lgkmcnt(0)
	s_barrier
	s_setprio 1
	s_waitcnt lgkmcnt(0)
	v_mfma_f32_16x16x32_bf16 v[126:129], v[152:155], v[184:187], v[126:129]
	v_mfma_f32_16x16x32_bf16 v[122:125], v[160:163], v[184:187], v[122:125]
	v_mfma_f32_16x16x32_bf16 v[110:113], v[152:155], v[192:195], v[110:113]
	v_mfma_f32_16x16x32_bf16 v[106:109], v[160:163], v[192:195], v[106:109]
	v_mfma_f32_16x16x32_bf16 v[94:97], v[152:155], v[200:203], v[94:97]
	v_mfma_f32_16x16x32_bf16 v[90:93], v[160:163], v[200:203], v[90:93]
	v_mfma_f32_16x16x32_bf16 v[78:81], v[152:155], v[208:211], v[78:81]
	v_mfma_f32_16x16x32_bf16 v[74:77], v[160:163], v[208:211], v[74:77]
	v_mfma_f32_16x16x32_bf16 v[126:129], v[156:159], v[188:191], v[126:129]
	v_mfma_f32_16x16x32_bf16 v[122:125], v[164:167], v[188:191], v[122:125]
	v_mfma_f32_16x16x32_bf16 v[110:113], v[156:159], v[196:199], v[110:113]
	v_mfma_f32_16x16x32_bf16 v[106:109], v[164:167], v[196:199], v[106:109]
	v_mfma_f32_16x16x32_bf16 v[94:97], v[156:159], v[204:207], v[94:97]
	v_mfma_f32_16x16x32_bf16 v[90:93], v[164:167], v[204:207], v[90:93]
	v_mfma_f32_16x16x32_bf16 v[78:81], v[156:159], v[212:215], v[78:81]
	v_mfma_f32_16x16x32_bf16 v[74:77], v[164:167], v[212:215], v[74:77]
	s_setprio 0
	s_setprio 1
	v_mfma_f32_16x16x32_bf16 v[118:121], v[168:171], v[184:187], v[118:121]
	v_mfma_f32_16x16x32_bf16 v[114:117], v[176:179], v[184:187], v[114:117]
	v_mfma_f32_16x16x32_bf16 v[102:105], v[168:171], v[192:195], v[102:105]
	v_mfma_f32_16x16x32_bf16 v[98:101], v[176:179], v[192:195], v[98:101]
	v_mfma_f32_16x16x32_bf16 v[86:89], v[168:171], v[200:203], v[86:89]
	v_mfma_f32_16x16x32_bf16 v[82:85], v[176:179], v[200:203], v[82:85]
	v_mfma_f32_16x16x32_bf16 v[70:73], v[168:171], v[208:211], v[70:73]
	v_mfma_f32_16x16x32_bf16 v[66:69], v[176:179], v[208:211], v[66:69]
	v_mfma_f32_16x16x32_bf16 v[118:121], v[172:175], v[188:191], v[118:121]
	v_mfma_f32_16x16x32_bf16 v[114:117], v[180:183], v[188:191], v[114:117]
	v_mfma_f32_16x16x32_bf16 v[102:105], v[172:175], v[196:199], v[102:105]
	v_mfma_f32_16x16x32_bf16 v[98:101], v[180:183], v[196:199], v[98:101]
	v_mfma_f32_16x16x32_bf16 v[86:89], v[172:175], v[204:207], v[86:89]
	v_mfma_f32_16x16x32_bf16 v[82:85], v[180:183], v[204:207], v[82:85]
	v_mfma_f32_16x16x32_bf16 v[70:73], v[172:175], v[212:215], v[70:73]
	v_mfma_f32_16x16x32_bf16 v[66:69], v[180:183], v[212:215], v[66:69]
	s_setprio 0
	s_barrier
	s_add_i32 s49, s40, s30
	s_mov_b32 m0, s49
	ds_read_b128 v[184:187], v151 offset:16384
	ds_read_b128 v[188:191], v151 offset:17408
	ds_read_b128 v[192:195], v151 offset:18432
	ds_read_b128 v[196:199], v151 offset:19456
	ds_read_b128 v[200:203], v151 offset:20480
	ds_read_b128 v[204:207], v151 offset:21504
	ds_read_b128 v[208:211], v151 offset:22528
	ds_read_b128 v[212:215], v151 offset:23552
	global_load_lds_dwordx4 v132, s[22:23]
	s_add_i32 m0, s49, 0x2000
	s_add_u32 s50, s22, 0x80000
	s_addc_u32 s51, s23, 0
	s_add_i32 s49, s41, s30
	global_load_lds_dwordx4 v136, s[22:23]
	s_mov_b32 m0, s49
	s_nop 0
	global_load_lds_dwordx4 v132, s[50:51]
	s_add_i32 m0, s49, 0x2000
	s_nop 0
	global_load_lds_dwordx4 v136, s[50:51]
	s_mov_b32 m0, s19
	s_nop 0
	global_load_lds_dwordx4 v130, s[24:25]
	s_mov_b32 m0, s33
	s_nop 0
	global_load_lds_dwordx4 v134, s[24:25]
	s_waitcnt vmcnt(8)
	s_waitcnt lgkmcnt(0)
	s_barrier
	s_setprio 1
	s_waitcnt lgkmcnt(0)
	v_mfma_f32_16x16x32_bf16 v[62:65], v[152:155], v[184:187], v[62:65]
	v_mfma_f32_16x16x32_bf16 v[58:61], v[160:163], v[184:187], v[58:61]
	v_mfma_f32_16x16x32_bf16 v[46:49], v[152:155], v[192:195], v[46:49]
	v_mfma_f32_16x16x32_bf16 v[42:45], v[160:163], v[192:195], v[42:45]
	v_mfma_f32_16x16x32_bf16 v[30:33], v[152:155], v[200:203], v[30:33]
	v_mfma_f32_16x16x32_bf16 v[26:29], v[160:163], v[200:203], v[26:29]
	v_mfma_f32_16x16x32_bf16 v[14:17], v[152:155], v[208:211], v[14:17]
	v_mfma_f32_16x16x32_bf16 v[10:13], v[160:163], v[208:211], v[10:13]
	v_mfma_f32_16x16x32_bf16 v[62:65], v[156:159], v[188:191], v[62:65]
	v_mfma_f32_16x16x32_bf16 v[58:61], v[164:167], v[188:191], v[58:61]
	v_mfma_f32_16x16x32_bf16 v[46:49], v[156:159], v[196:199], v[46:49]
	v_mfma_f32_16x16x32_bf16 v[42:45], v[164:167], v[196:199], v[42:45]
	v_mfma_f32_16x16x32_bf16 v[30:33], v[156:159], v[204:207], v[30:33]
	v_mfma_f32_16x16x32_bf16 v[26:29], v[164:167], v[204:207], v[26:29]
	v_mfma_f32_16x16x32_bf16 v[14:17], v[156:159], v[212:215], v[14:17]
	v_mfma_f32_16x16x32_bf16 v[10:13], v[164:167], v[212:215], v[10:13]
	s_setprio 0
	s_setprio 1
	v_mfma_f32_16x16x32_bf16 v[54:57], v[168:171], v[184:187], v[54:57]
	v_mfma_f32_16x16x32_bf16 v[50:53], v[176:179], v[184:187], v[50:53]
	v_mfma_f32_16x16x32_bf16 v[38:41], v[168:171], v[192:195], v[38:41]
	v_mfma_f32_16x16x32_bf16 v[34:37], v[176:179], v[192:195], v[34:37]
	v_mfma_f32_16x16x32_bf16 v[22:25], v[168:171], v[200:203], v[22:25]
	v_mfma_f32_16x16x32_bf16 v[18:21], v[176:179], v[200:203], v[18:21]
	v_mfma_f32_16x16x32_bf16 v[6:9], v[168:171], v[208:211], v[6:9]
	v_mfma_f32_16x16x32_bf16 v[2:5], v[176:179], v[208:211], v[2:5]
	v_mfma_f32_16x16x32_bf16 v[54:57], v[172:175], v[188:191], v[54:57]
	v_mfma_f32_16x16x32_bf16 v[50:53], v[180:183], v[188:191], v[50:53]
	v_mfma_f32_16x16x32_bf16 v[38:41], v[172:175], v[196:199], v[38:41]
	v_mfma_f32_16x16x32_bf16 v[34:37], v[180:183], v[196:199], v[34:37]
	v_mfma_f32_16x16x32_bf16 v[22:25], v[172:175], v[204:207], v[22:25]
	v_mfma_f32_16x16x32_bf16 v[18:21], v[180:183], v[204:207], v[18:21]
	v_mfma_f32_16x16x32_bf16 v[6:9], v[172:175], v[212:215], v[6:9]
	v_mfma_f32_16x16x32_bf16 v[2:5], v[180:183], v[212:215], v[2:5]
	s_setprio 0
	s_barrier
	s_add_i32 s49, 0, 0x18000
	s_add_i32 s50, 0, 0x1c000
	v_add_u32_e32 v164, s49, v147
	v_add_u32_e32 v180, s50, v147
	ds_read_b128 v[152:155], v164
	ds_read_b128 v[156:159], v164 offset:1024
	ds_read_b128 v[160:163], v164 offset:2048
	ds_read_b128 v[164:167], v164 offset:3072
	ds_read_b128 v[168:171], v180
	ds_read_b128 v[172:175], v180 offset:1024
	ds_read_b128 v[176:179], v180 offset:2048
	ds_read_b128 v[180:183], v180 offset:3072
	s_add_u32 s24, s24, 0x80000
	s_addc_u32 s25, s25, 0
	s_add_u32 s100, s24, 0xfff80080
	s_addc_u32 s101, s25, -1
	s_mov_b32 m0, s34
	ds_read_b128 v[184:187], v151 offset:32768
	ds_read_b128 v[188:191], v151 offset:33792
	ds_read_b128 v[192:195], v151 offset:34816
	ds_read_b128 v[196:199], v151 offset:35840
	ds_read_b128 v[200:203], v151 offset:36864
	ds_read_b128 v[204:207], v151 offset:37888
	ds_read_b128 v[208:211], v151 offset:38912
	ds_read_b128 v[212:215], v151 offset:39936
	global_load_lds_dwordx4 v130, s[24:25]
	s_mov_b32 m0, s35
	s_nop 0
	global_load_lds_dwordx4 v134, s[24:25]
	s_waitcnt vmcnt(8)
	s_waitcnt lgkmcnt(0)
	s_barrier
	s_setprio 1
	s_waitcnt lgkmcnt(0)
	v_mfma_f32_16x16x32_bf16 v[126:129], v[152:155], v[184:187], v[126:129]
	v_mfma_f32_16x16x32_bf16 v[122:125], v[160:163], v[184:187], v[122:125]
	v_mfma_f32_16x16x32_bf16 v[110:113], v[152:155], v[192:195], v[110:113]
	v_mfma_f32_16x16x32_bf16 v[106:109], v[160:163], v[192:195], v[106:109]
	v_mfma_f32_16x16x32_bf16 v[94:97], v[152:155], v[200:203], v[94:97]
	v_mfma_f32_16x16x32_bf16 v[90:93], v[160:163], v[200:203], v[90:93]
	v_mfma_f32_16x16x32_bf16 v[78:81], v[152:155], v[208:211], v[78:81]
	v_mfma_f32_16x16x32_bf16 v[74:77], v[160:163], v[208:211], v[74:77]
	v_mfma_f32_16x16x32_bf16 v[126:129], v[156:159], v[188:191], v[126:129]
	v_mfma_f32_16x16x32_bf16 v[122:125], v[164:167], v[188:191], v[122:125]
	v_mfma_f32_16x16x32_bf16 v[110:113], v[156:159], v[196:199], v[110:113]
	v_mfma_f32_16x16x32_bf16 v[106:109], v[164:167], v[196:199], v[106:109]
	v_mfma_f32_16x16x32_bf16 v[94:97], v[156:159], v[204:207], v[94:97]
	v_mfma_f32_16x16x32_bf16 v[90:93], v[164:167], v[204:207], v[90:93]
	v_mfma_f32_16x16x32_bf16 v[78:81], v[156:159], v[212:215], v[78:81]
	v_mfma_f32_16x16x32_bf16 v[74:77], v[164:167], v[212:215], v[74:77]
	s_setprio 0
	s_setprio 1
	v_mfma_f32_16x16x32_bf16 v[118:121], v[168:171], v[184:187], v[118:121]
	v_mfma_f32_16x16x32_bf16 v[114:117], v[176:179], v[184:187], v[114:117]
	v_mfma_f32_16x16x32_bf16 v[102:105], v[168:171], v[192:195], v[102:105]
	v_mfma_f32_16x16x32_bf16 v[98:101], v[176:179], v[192:195], v[98:101]
	v_mfma_f32_16x16x32_bf16 v[86:89], v[168:171], v[200:203], v[86:89]
	v_mfma_f32_16x16x32_bf16 v[82:85], v[176:179], v[200:203], v[82:85]
	v_mfma_f32_16x16x32_bf16 v[70:73], v[168:171], v[208:211], v[70:73]
	v_mfma_f32_16x16x32_bf16 v[66:69], v[176:179], v[208:211], v[66:69]
	v_mfma_f32_16x16x32_bf16 v[118:121], v[172:175], v[188:191], v[118:121]
	v_mfma_f32_16x16x32_bf16 v[114:117], v[180:183], v[188:191], v[114:117]
	v_mfma_f32_16x16x32_bf16 v[102:105], v[172:175], v[196:199], v[102:105]
	v_mfma_f32_16x16x32_bf16 v[98:101], v[180:183], v[196:199], v[98:101]
	v_mfma_f32_16x16x32_bf16 v[86:89], v[172:175], v[204:207], v[86:89]
	v_mfma_f32_16x16x32_bf16 v[82:85], v[180:183], v[204:207], v[82:85]
	v_mfma_f32_16x16x32_bf16 v[70:73], v[172:175], v[212:215], v[70:73]
	v_mfma_f32_16x16x32_bf16 v[66:69], v[180:183], v[212:215], v[66:69]
	s_setprio 0
	s_barrier
	s_add_i32 s24, s49, s30
	s_mov_b32 m0, s24
	ds_read_b128 v[184:187], v151 offset:49152
	ds_read_b128 v[188:191], v151 offset:50176
	ds_read_b128 v[192:195], v151 offset:51200
	ds_read_b128 v[196:199], v151 offset:52224
	ds_read_b128 v[200:203], v151 offset:53248
	ds_read_b128 v[204:207], v151 offset:54272
	ds_read_b128 v[208:211], v151 offset:55296
	ds_read_b128 v[212:215], v151 offset:56320
	s_add_u32 s98, s22, 0x80
	s_addc_u32 s99, s23, 0
	global_load_lds_dwordx4 v132, s[98:99]
	s_add_i32 m0, s24, 0x2000
	s_add_u32 s22, s22, 0x80080
	s_addc_u32 s23, s23, 0
	s_add_i32 s24, s50, s30
	global_load_lds_dwordx4 v136, s[98:99]
	s_mov_b32 m0, s24
	s_nop 0
	global_load_lds_dwordx4 v132, s[22:23]
	s_add_i32 m0, s24, 0x2000
	s_nop 0
	global_load_lds_dwordx4 v136, s[22:23]
	s_mov_b32 m0, s38
	s_nop 0
	global_load_lds_dwordx4 v130, s[100:101]
	s_mov_b32 m0, s39
	s_nop 0
	global_load_lds_dwordx4 v134, s[100:101]
	s_waitcnt vmcnt(8)
	s_waitcnt lgkmcnt(0)
	s_barrier
	s_setprio 1
	s_waitcnt lgkmcnt(0)
	v_mfma_f32_16x16x32_bf16 v[62:65], v[152:155], v[184:187], v[62:65]
	v_mfma_f32_16x16x32_bf16 v[58:61], v[160:163], v[184:187], v[58:61]
	v_mfma_f32_16x16x32_bf16 v[46:49], v[152:155], v[192:195], v[46:49]
	v_mfma_f32_16x16x32_bf16 v[42:45], v[160:163], v[192:195], v[42:45]
	v_mfma_f32_16x16x32_bf16 v[30:33], v[152:155], v[200:203], v[30:33]
	v_mfma_f32_16x16x32_bf16 v[26:29], v[160:163], v[200:203], v[26:29]
	v_mfma_f32_16x16x32_bf16 v[14:17], v[152:155], v[208:211], v[14:17]
	v_mfma_f32_16x16x32_bf16 v[10:13], v[160:163], v[208:211], v[10:13]
	v_mfma_f32_16x16x32_bf16 v[62:65], v[156:159], v[188:191], v[62:65]
	v_mfma_f32_16x16x32_bf16 v[58:61], v[164:167], v[188:191], v[58:61]
	v_mfma_f32_16x16x32_bf16 v[46:49], v[156:159], v[196:199], v[46:49]
	v_mfma_f32_16x16x32_bf16 v[42:45], v[164:167], v[196:199], v[42:45]
	v_mfma_f32_16x16x32_bf16 v[30:33], v[156:159], v[204:207], v[30:33]
	v_mfma_f32_16x16x32_bf16 v[26:29], v[164:167], v[204:207], v[26:29]
	v_mfma_f32_16x16x32_bf16 v[14:17], v[156:159], v[212:215], v[14:17]
	v_mfma_f32_16x16x32_bf16 v[10:13], v[164:167], v[212:215], v[10:13]
	s_setprio 0
	s_setprio 1
	v_mfma_f32_16x16x32_bf16 v[54:57], v[168:171], v[184:187], v[54:57]
	v_mfma_f32_16x16x32_bf16 v[50:53], v[176:179], v[184:187], v[50:53]
	v_mfma_f32_16x16x32_bf16 v[38:41], v[168:171], v[192:195], v[38:41]
	v_mfma_f32_16x16x32_bf16 v[34:37], v[176:179], v[192:195], v[34:37]
	v_mfma_f32_16x16x32_bf16 v[22:25], v[168:171], v[200:203], v[22:25]
	v_mfma_f32_16x16x32_bf16 v[18:21], v[176:179], v[200:203], v[18:21]
	v_mfma_f32_16x16x32_bf16 v[6:9], v[168:171], v[208:211], v[6:9]
	v_mfma_f32_16x16x32_bf16 v[2:5], v[176:179], v[208:211], v[2:5]
	v_mfma_f32_16x16x32_bf16 v[54:57], v[172:175], v[188:191], v[54:57]
	v_mfma_f32_16x16x32_bf16 v[50:53], v[180:183], v[188:191], v[50:53]
	v_mfma_f32_16x16x32_bf16 v[38:41], v[172:175], v[196:199], v[38:41]
	v_mfma_f32_16x16x32_bf16 v[34:37], v[180:183], v[196:199], v[34:37]
	v_mfma_f32_16x16x32_bf16 v[22:25], v[172:175], v[204:207], v[22:25]
	v_mfma_f32_16x16x32_bf16 v[18:21], v[180:183], v[204:207], v[18:21]
	v_mfma_f32_16x16x32_bf16 v[6:9], v[172:175], v[212:215], v[6:9]
	v_mfma_f32_16x16x32_bf16 v[2:5], v[180:183], v[212:215], v[2:5]
	s_setprio 0
	s_barrier
	s_add_i32 s48, s48, 2
	s_add_u32 s20, s20, 0x100
	s_addc_u32 s21, s21, 0
	s_add_u32 s46, s46, 0x100
	s_addc_u32 s47, s47, 0
	s_cmp_gt_u32 s48, 29
	s_cbranch_scc0 .LBB0_1135
	v_readlane_b32 s44, v254, 52
	s_and_b64 vcc, exec, s[8:9]
	v_readlane_b32 s45, v254, 53
	v_readlane_b32 s46, v254, 54
	v_readlane_b32 s47, v254, 55
	s_cbranch_vccz .LBB0_1138
	s_barrier
